# v16 + loop-invariant gain loads hoisted out of the final rmsnorm loop
# baseline (speedup 1.0000x reference)
; __device__ __forceinline__ float bflo(unsigned u) { return __uint_as_float(u << 16); }
; __device__ __forceinline__ float bfhi(unsigned u) { return __uint_as_float(u & 0xffff0000u); }
; __global__ void __launch_bounds__(NTHR, 2) hymba_fwd(Args args) {
;     ...
;     { const int l = 0; PH_BEGIN
;         const float* fg = ap->in[19];
;         for (int j = 0; j < 16; ++j) { const int m = (cx % 8) * 4096 + ((cx / 8) * 8 + wave) * 16 + j;
;             const v4u w0 = *(const v4u*)(XB + (size_t)m * DM + lane * 16), w1 = *(const v4u*)(XB + (size_t)m * DM + lane * 16 + 8);
;             const unsigned ww[8] = {w0.x, w0.y, w0.z, w0.w, w1.x, w1.y, w1.z, w1.w};
;             float v[16]; float sq = 0.f;
; #pragma unroll
;             for (int i = 0; i < 8; ++i) { v[2 * i] = bflo(ww[i]); v[2 * i + 1] = bfhi(ww[i]); sq += v[2 * i] * v[2 * i] + v[2 * i + 1] * v[2 * i + 1]; }
;             const float r = 1.0f / sqrtf(wave_sum(sq) * (1.0f / DM) + EPS);
;             f32x4* op = (f32x4*)(X + (size_t)m * DM + lane * 16); const f32x4* gp = (const f32x4*)(fg + lane * 16);
; #pragma unroll
;             for (int i = 0; i < 4; ++i) { const f32x4 g4 = gp[i]; op[i] = (f32x4){v[4 * i] * r * g4[0], v[4 * i + 1] * r * g4[1], v[4 * i + 2] * r * g4[2], v[4 * i + 3] * r * g4[3]}; }
;         }
;     }
.LBB0_946:
	s_mov_b32 s2, 0
	v_mov_b32_e32 v0, 0x20174
	s_load_dwordx4 s[4:7], s[0:1], 0x98
	s_load_dwordx2 s[2:3], s[0:1], 0xa8
	v_readfirstlane_b32 s0, v204
	v_add_u32_e32 v0, 0, v0
	ds_read_b32 v0, v0
	s_ashr_i32 s0, s0, 6
	v_mov_b32_e32 v5, 0
	v_and_b32_e32 v6, 63, v204
	v_mov_b32_e32 v7, 0x260
	s_waitcnt lgkmcnt(0)
	v_readfirstlane_b32 s1, v0
	s_lshl_b32 s8, s1, 12
	s_and_b32 s1, s1, 0xf8
	s_add_i32 s1, s1, s0
	s_and_b32 s8, s8, 0x7000
	s_lshl_b32 s0, s1, 4
	s_add_i32 s0, s0, s8
	v_lshlrev_b32_e32 v0, 6, v204
	v_and_b32_e32 v4, 0xfc0, v0
	s_ashr_i32 s1, s0, 31
	v_lshl_add_u64 v[0:1], s[4:5], 0, v[4:5]
	s_lshl_b64 s[4:5], s[0:1], 11
	s_add_u32 s2, s2, s4
	s_addc_u32 s3, s3, s5
	s_lshl_b64 s[0:1], s[0:1], 12
	v_lshlrev_b32_e32 v4, 5, v6
	s_add_u32 s0, s6, s0
	v_lshl_add_u64 v[2:3], s[2:3], 0, v[4:5]
	v_lshlrev_b32_e32 v4, 6, v6
	s_addc_u32 s1, s7, s1
	v_lshl_add_u64 v[4:5], s[0:1], 0, v[4:5]
	v_lshl_add_u64 v[4:5], v[4:5], 0, 32
	s_mov_b64 s[2:3], 0
	s_mov_b64 s[4:5], 0xa400000
	v_mov_b32_e32 v6, 0x358637bd
	s_mov_b32 s8, 0xf800000
	s_mov_b64 s[6:7], 0x1000
	global_load_dwordx4 v[44:47], v[0:1], off
	global_load_dwordx4 v[48:51], v[0:1], off offset:16
	global_load_dwordx4 v[52:55], v[0:1], off offset:32
	global_load_dwordx4 v[56:59], v[0:1], off offset:48
.LBB0_947:
	v_lshl_add_u64 v[8:9], v[2:3], 0, s[2:3]
	v_add_co_u32_e32 v22, vcc, 0xa400000, v8
	v_lshl_add_u64 v[20:21], v[8:9], 0, s[4:5]
	s_nop 0
	v_addc_co_u32_e32 v23, vcc, 0, v9, vcc
	global_load_dwordx4 v[8:11], v[22:23], off
	global_load_dwordx4 v[12:15], v[20:21], off offset:16
	s_add_u32 s2, s2, 0x800
	s_addc_u32 s3, s3, 0
	s_cmpk_eq_u32 s2, 0x8000
	s_waitcnt vmcnt(1)
	v_lshlrev_b32_e32 v20, 16, v8
	v_and_b32_e32 v21, 0xffff0000, v8
	v_lshlrev_b32_e32 v8, 16, v9
	v_and_b32_e32 v9, 0xffff0000, v9
	v_lshlrev_b32_e32 v22, 16, v10
	v_and_b32_e32 v23, 0xffff0000, v10
	v_lshlrev_b32_e32 v24, 16, v11
	v_and_b32_e32 v25, 0xffff0000, v11
	v_pk_mul_f32 v[10:11], v[20:21], v[20:21]
	v_pk_mul_f32 v[30:31], v[8:9], v[8:9]
	v_pk_mul_f32 v[32:33], v[22:23], v[22:23]
	v_add_f32_e32 v30, v30, v31
	v_add_f32_e32 v10, v10, v11
	s_waitcnt vmcnt(0)
	v_lshlrev_b32_e32 v26, 16, v12
	v_and_b32_e32 v27, 0xffff0000, v12
	v_pk_mul_f32 v[34:35], v[24:25], v[24:25]
	v_add_f32_e32 v11, v32, v33
	v_add_f32_e32 v10, v10, v30
	v_lshlrev_b32_e32 v12, 16, v13
	v_and_b32_e32 v13, 0xffff0000, v13
	v_pk_mul_f32 v[36:37], v[26:27], v[26:27]
	v_add_f32_e32 v34, v34, v35
	v_add_f32_e32 v10, v10, v11
	v_lshlrev_b32_e32 v28, 16, v14
	v_and_b32_e32 v29, 0xffff0000, v14
	v_pk_mul_f32 v[38:39], v[12:13], v[12:13]
	v_add_f32_e32 v31, v36, v37
	v_add_f32_e32 v10, v10, v34
	v_lshlrev_b32_e32 v14, 16, v15
	v_and_b32_e32 v15, 0xffff0000, v15
	v_pk_mul_f32 v[40:41], v[28:29], v[28:29]
	v_add_f32_e32 v32, v38, v39
	v_add_f32_e32 v10, v10, v31
	v_pk_mul_f32 v[42:43], v[14:15], v[14:15]
	v_add_f32_e32 v33, v40, v41
	v_add_f32_e32 v10, v10, v32
	v_add_f32_e32 v35, v42, v43
	v_add_f32_e32 v10, v10, v33
	v_add_f32_e32 v10, v10, v35
	ds_swizzle_b32 v11, v10 offset:swizzle(SWAP,1)
	s_waitcnt lgkmcnt(0)
	v_add_f32_e32 v10, v10, v11
	ds_swizzle_b32 v11, v10 offset:swizzle(SWAP,2)
	s_waitcnt lgkmcnt(0)
	v_add_f32_e32 v10, v10, v11
	ds_swizzle_b32 v11, v10 offset:swizzle(SWAP,4)
	s_waitcnt lgkmcnt(0)
	v_add_f32_e32 v10, v10, v11
	ds_swizzle_b32 v11, v10 offset:swizzle(SWAP,8)
	s_waitcnt lgkmcnt(0)
	v_add_f32_e32 v10, v10, v11
	ds_swizzle_b32 v11, v10 offset:swizzle(SWAP,16)
	s_waitcnt lgkmcnt(0)
	v_add_f32_e32 v10, v10, v11
	v_mov_b32_e32 v11, v10
	s_nop 1
	v_permlane32_swap_b32_e32 v10, v11
	v_add_f32_e32 v10, v10, v11
	v_fmamk_f32 v10, v10, 0x3a800000, v6
	v_mul_f32_e32 v11, 0x4f800000, v10
	v_cmp_gt_f32_e32 vcc, s8, v10
	s_nop 1
	v_cndmask_b32_e32 v10, v10, v11, vcc
	v_sqrt_f32_e32 v11, v10
	s_nop 0
	v_add_u32_e32 v30, -1, v11
	v_add_u32_e32 v31, 1, v11
	v_fma_f32 v32, -v30, v11, v10
	v_fma_f32 v33, -v31, v11, v10
	v_cmp_ge_f32_e64 s[0:1], 0, v32
	s_nop 1
	v_cndmask_b32_e64 v11, v11, v30, s[0:1]
	v_cmp_lt_f32_e64 s[0:1], 0, v33
	s_nop 1
	v_cndmask_b32_e64 v11, v11, v31, s[0:1]
	v_mul_f32_e32 v30, 0x37800000, v11
	v_cndmask_b32_e32 v11, v11, v30, vcc
	v_cmp_class_f32_e32 vcc, v10, v7
	s_nop 1
	v_cndmask_b32_e32 v10, v11, v10, vcc
	v_div_scale_f32 v11, s[0:1], v10, v10, 1.0
	v_rcp_f32_e32 v31, v11
	v_div_scale_f32 v30, vcc, 1.0, v10, 1.0
	v_fma_f32 v32, -v11, v31, 1.0
	v_fmac_f32_e32 v31, v32, v31
	v_mul_f32_e32 v32, v30, v31
	v_fma_f32 v33, -v11, v32, v30
	v_fmac_f32_e32 v32, v33, v31
	v_fma_f32 v11, -v11, v32, v30
	v_div_fmas_f32 v11, v11, v31, v32
	v_div_fixup_f32 v30, v11, v10, 1.0
	v_pk_mul_f32 v[20:21], v[30:31], v[20:21] op_sel_hi:[0,1]
	v_pk_mul_f32 v[8:9], v[30:31], v[8:9] op_sel_hi:[0,1]
	v_pk_mul_f32 v[10:11], v[8:9], v[46:47]
	v_pk_mul_f32 v[8:9], v[20:21], v[44:45]
	global_store_dwordx4 v[4:5], v[8:11], off offset:-32
	v_pk_mul_f32 v[16:17], v[30:31], v[24:25] op_sel_hi:[0,1]
	v_pk_mul_f32 v[18:19], v[30:31], v[22:23] op_sel_hi:[0,1]
	v_pk_mul_f32 v[12:13], v[30:31], v[12:13] op_sel_hi:[0,1]
	v_pk_mul_f32 v[8:9], v[18:19], v[48:49]
	v_pk_mul_f32 v[10:11], v[16:17], v[50:51]
	global_store_dwordx4 v[4:5], v[8:11], off offset:-16
	v_pk_mul_f32 v[16:17], v[30:31], v[26:27] op_sel_hi:[0,1]
	s_nop 0
	v_pk_mul_f32 v[8:9], v[16:17], v[52:53]
	v_pk_mul_f32 v[10:11], v[12:13], v[54:55]
	global_store_dwordx4 v[4:5], v[8:11], off
	v_pk_mul_f32 v[12:13], v[30:31], v[14:15] op_sel_hi:[0,1]
	v_pk_mul_f32 v[14:15], v[30:31], v[28:29] op_sel_hi:[0,1]
	v_pk_mul_f32 v[8:9], v[14:15], v[56:57]
	v_pk_mul_f32 v[10:11], v[12:13], v[58:59]
	global_store_dwordx4 v[4:5], v[8:11], off offset:16
	v_lshl_add_u64 v[4:5], v[4:5], 0, s[6:7]
	s_cbranch_scc0 .LBB0_947
	s_endpgm
